# ret scan: odd blocks run their sample units before the prompt chain (state traffic of the two halves no longer coincides)
# speedup vs baseline: 1.0016x; 1.0016x over previous
; __device__ __forceinline__ int BID() { int t = blockIdx.x; asm volatile("" : "+s"(t)); return t; }
; __device__ __forceinline__ void ret_block(ArgsP a_, unsigned char* smem) { const ArgsP a = a_;
;     ...
;     const int G = gridDim.x, cb0 = BID();
;     const int cb = (G == 256) ? ((((cb0 & 7) * 4 + (cb0 >> 6)) << 3) | ((cb0 >> 3) & 7)) : cb0;
;     const unsigned char* proj = a->ws + B_PROJ;
;     const bf16_t* Qg = (const bf16_t*)proj; const bf16_t* Kg = (const bf16_t*)(proj + (size_t)MP * 2048); const bf16_t* Vg = (const bf16_t*)(proj + (size_t)MP * 4096);
;     bf16_t* OB = (bf16_t*)(a->ws + B_PART);
;     const int np = cb < 256 ? 33 : 0;
;     const int s0 = cb < 256 ? cb : cb - 256;
;     const int nsmp = (4096 - (cb % 256) + G - 1) / G;
;     const int nunits = np + nsmp;
;     f32x4 S[2][4]; f32x4 O[2];
;     u32x4 qpre[4], kpre[4]; bf16_t vpre[8];
;     const int vv = tid & 63, jg = tid >> 6;
;     ...
;     (void)s0;
;     if (nunits > 0) RT_LOAD(0);
;     const int ntot_ = np + nsmp * REP_SMP;
.LBB0_224:
	s_load_dwordx2 s[26:27], s[4:5], 0xe0
	v_ashrrev_i32_e32 v19, 6, v97
	v_and_b32_e32 v18, 63, v97
	s_waitcnt lgkmcnt(0)
	s_add_u32 s22, s26, 0x208e0000
	s_addc_u32 s23, s27, 0
	s_add_u32 s24, s26, 0x22b60000
	s_addc_u32 s25, s27, 0
	s_add_u32 s75, s26, 0x24de0000
	s_addc_u32 s76, s27, 0
	s_cmpk_gt_i32 s74, 0xff
	s_cselect_b64 s[40:41], -1, 0
	s_cmpk_lt_i32 s74, 0x100
	s_cselect_b32 s77, 33, 0
	s_abs_i32 s35, s13
	v_cvt_f32_u32_e32 v0, s35
	s_ashr_i32 s34, s74, 31
	s_lshr_b32 s34, s34, 24
	s_add_i32 s34, s74, s34
	v_rcp_iflag_f32_e32 v0, v0
	s_and_b32 s34, s34, 0xffffff00
	s_sub_i32 s78, s74, s34
	s_sub_i32 s34, s13, s78
	v_mul_f32_e32 v0, 0x4f7ffffe, v0
	v_cvt_u32_f32_e32 v0, v0
	s_addk_i32 s34, 0xfff
	s_xor_b32 s42, s34, s13
	s_ashr_i32 s64, s42, 31
	s_sub_i32 s42, 0, s35
	v_readfirstlane_b32 s43, v0
	s_mul_i32 s42, s42, s43
	s_mul_hi_u32 s42, s43, s42
	s_abs_i32 s34, s34
	s_add_i32 s43, s43, s42
	s_mul_hi_u32 s42, s34, s43
	s_mul_i32 s43, s42, s35
	s_sub_i32 s34, s34, s43
	s_add_i32 s43, s42, 1
	s_sub_i32 s44, s34, s35
	s_cmp_ge_u32 s34, s35
	s_cselect_b32 s42, s43, s42
	s_cselect_b32 s34, s44, s34
	s_add_i32 s43, s42, 1
	s_cmp_ge_u32 s34, s35
	s_cselect_b32 s34, s43, s42
	s_xor_b32 s65, s34, s64
	s_sub_i32 s66, s65, s64
	s_add_i32 s79, s77, s66
	s_cmp_gt_i32 s79, 0
	s_cselect_b64 s[34:35], -1, 0
	s_cmp_lt_i32 s79, 1
	s_cbranch_scc1 .LBB0_230
	s_mov_b64 s[42:43], -1
	s_bitcmp1_b32 s74, 0
	s_cselect_b64 s[40:41], -1, s[40:41]
	s_and_b64 vcc, exec, s[40:41]
	s_cbranch_vccz .LBB0_227
	s_lshr_b32 s40, s78, 2
	s_and_b32 s40, s40, 56
	s_or_b32 s40, s40, 0x4080
	s_mov_b64 s[42:43], 0

; #define RT_DECODE(u, b_, h_, vs_, ck_, smp_, row0_, len_) do { if ((u) < np) { b_ = cb >> 5; h_ = (cb >> 3) & 3; vs_ = cb & 7; ck_ = (u); smp_ = false; row0_ = b_ * TP + 64 * ck_; len_ = ck_ < 32 ? 64 : 16; } \
;         else { const int it_ = (cb % 256) + ((u) - np) * G; b_ = it_ >> 5; h_ = (it_ >> 3) & 3; vs_ = it_ & 7; ck_ = 0; smp_ = true; row0_ = RP + 8 * b_; len_ = 8; } } while (0)
; __device__ __forceinline__ void ret_block(ArgsP a_, unsigned char* smem) { const ArgsP a = a_;
;     ...
;     for (int uu = 0; uu < ntot_; ++uu) { const int u = uu < np ? uu : np + (uu - np) % nsmp; const int un_ = uu + 1 < np ? uu + 1 : np + (uu + 1 - np) % nsmp;
;         int b, h, vs, ck, row0, len; bool sample; RT_DECODE(u, b, h, vs, ck, sample, row0, len);
.LBB0_237:
	s_bitcmp1_b32 s74, 0
	s_cbranch_scc0 .Lret_norot
	s_add_i32 s64, s86, -1
	s_add_i32 s65, s64, s77
	s_sub_i32 s66, s64, s82
	s_cmp_lt_u32 s64, s82
	s_cselect_b32 s87, s65, s66
	s_add_i32 s65, s86, s77
	s_sub_i32 s66, s86, s82
	s_cmp_lt_u32 s86, s82
	s_cselect_b32 s92, s65, s66
